# ffn-in GEMM: next tile's row-scale loads hoisted above the epilogue; prep waits with counted vmcnt
# speedup vs baseline: 1.0002x; 1.0002x over previous
; #define LAS __attribute__((address_space(3)))
; __device__ __forceinline__ unsigned cvt_pk_bf16(float lo, float hi) { unsigned r; asm volatile("v_cvt_pk_bf16_f32 %0, %1, %2" : "=v"(r) : "v"(lo), "v"(hi)); return r; }
; __device__ __forceinline__ float sigmoidf_(float v) { return __builtin_amdgcn_rcpf(1.f + __expf(-v)); }
;     __device__ __forceinline__ void prep(const pg8::Unit& u, LAS unsigned char* sp, int tid) const {
;         if (tid < 256) ((LAS float*)sp)[tid] = row_scale(ssq, u.pm * 256 + tid);
;     __device__ __forceinline__ void operator()(const f32x4 (&acc)[2][2][4][2], const pg8::Unit& u, int wr, int wc, int fr, int fq, LAS unsigned char* sp) const {
;     ...
;         for (int ai = 0; ai < 2; ++ai)
; #pragma unroll
;             for (int m = 0; m < 4; ++m) {
;                 const int row = row0 + ai * 128 + m * 16; const float s = rsl[ai * 128 + m * 16];
; #pragma unroll
;                 for (int bj = 0; bj < 2; ++bj) {
;                     f32x4 v0 = acc[ai][bj][m][0] * s, v1 = acc[ai][bj][m][1] * s;
;                     const int col = colt + bj * 128 + cw0;
;                     if (act == 2) { const f32x4 b0 = *(const LAS f32x4*)(bsl + bj * 128 + cw0), b1 = *(const LAS f32x4*)(bsl + bj * 128 + cw0 + 4);
;                         v0 += b0; v1 += b1;
; #pragma unroll
;                         for (int j = 0; j < 4; ++j) { v0[j] = sigmoidf_(v0[j]); v1[j] = sigmoidf_(v1[j]); } }
;                     else if (act == 1) {
; #pragma unroll
;                         for (int j = 0; j < 4; ++j) { v0[j] = v0[j] * sigmoidf_(v0[j]); v1[j] = v1[j] * sigmoidf_(v1[j]); } }
;                     u32x4 w; w.x = cvt_pk_bf16(v0[0], v0[1]); w.y = cvt_pk_bf16(v0[2], v0[3]); w.z = cvt_pk_bf16(v1[0], v1[1]); w.w = cvt_pk_bf16(v1[2], v1[3]);
;                     *(u32x4*)(dst + (size_t)row * pitch + col) = w;
.LBB0_33:
	s_and_b64 s[84:85], s[4:5], s[6:7]
	s_and_saveexec_b64 s[88:89], s[84:85]
	s_cbranch_execz .Lpre6_skip
	v_lshl_add_u32 v214, s22, 8, v144
	v_ashrrev_i32_e32 v215, 31, v214
	v_lshlrev_b64 v[214:215], 6, v[214:215]
	v_lshl_add_u64 v[214:215], v[130:131], 0, v[214:215]
	global_load_dwordx4 v[198:201], v[214:215], off offset:48
	global_load_dwordx4 v[202:205], v[214:215], off offset:32
	global_load_dwordx4 v[206:209], v[214:215], off offset:16
	global_load_dwordx4 v[210:213], v[214:215], off
.Lpre6_skip:
	s_mov_b64 exec, s[88:89]
	s_lshl_b32 s19, s69, 11
	s_and_b32 s19, s19, 0x800
	v_add_u32_e32 v161, s19, v157
	s_lshl_b32 s19, s68, 8
	s_add_i32 s23, s19, 0xfffff500
	ds_read_b32 v162, v161
	s_cmp_lt_i32 s68, 11
	s_cselect_b32 s19, s19, s23
	s_cselect_b32 s23, 0, 0xb000000
	s_add_u32 s26, s61, s23
	s_addc_u32 s27, s62, 0
	v_lshl_add_u32 v163, s52, 8, v145
	v_or_b32_e32 v164, s19, v159
	v_mov_b64_e32 v[142:143], s[26:27]
	s_waitcnt lgkmcnt(0)
	v_pk_mul_f32 v[126:127], v[126:127], v[162:163] op_sel_hi:[1,0]
	v_pk_mul_f32 v[122:123], v[122:123], v[162:163] op_sel_hi:[1,0]
	v_ashrrev_i32_e32 v165, 31, v164
	v_mad_i64_i32 v[166:167], s[26:27], v163, s31, v[142:143]
	v_pk_mul_f32 v[128:129], v[128:129], v[162:163] op_sel_hi:[1,0]
	v_pk_mul_f32 v[168:169], v[124:125], v[162:163] op_sel_hi:[1,0]
	v_cvt_pk_bf16_f32 v124, v126, v127
	v_cvt_pk_bf16_f32 v125, v128, v129
	v_cvt_pk_bf16_f32 v126, v122, v123
	v_lshlrev_b64 v[122:123], 1, v[164:165]
	v_lshl_add_u64 v[128:129], v[166:167], 0, v[122:123]
	v_cvt_pk_bf16_f32 v127, v168, v169
	global_store_dwordx4 v[128:129], v[124:127], off nt
	v_pk_mul_f32 v[118:119], v[118:119], v[162:163] op_sel_hi:[1,0]
	v_pk_mul_f32 v[120:121], v[120:121], v[162:163] op_sel_hi:[1,0]
	v_pk_mul_f32 v[124:125], v[112:113], v[162:163] op_sel_hi:[1,0]
	v_pk_mul_f32 v[112:113], v[110:111], v[162:163] op_sel_hi:[1,0]
	v_cvt_pk_bf16_f32 v110, v118, v119
	v_cvt_pk_bf16_f32 v111, v120, v121
	s_andn2_b64 vcc, exec, s[6:7]
	v_cvt_pk_bf16_f32 v112, v112, v113
	v_cvt_pk_bf16_f32 v113, v124, v125
	ds_read_b32 v118, v161 offset:64
	global_store_dwordx4 v[128:129], v[110:113], off offset:256 nt
	s_mov_b64 s[6:7], -1
	s_waitcnt lgkmcnt(0)
	v_pk_mul_f32 v[114:115], v[114:115], v[118:119] op_sel_hi:[1,0]
	v_or_b32_e32 v110, 16, v163
	v_mad_i64_i32 v[110:111], s[26:27], v110, s31, v[142:143]
	v_pk_mul_f32 v[112:113], v[116:117], v[118:119] op_sel_hi:[1,0]
	v_pk_mul_f32 v[116:117], v[108:109], v[118:119] op_sel_hi:[1,0]
	v_pk_mul_f32 v[108:109], v[106:107], v[118:119] op_sel_hi:[1,0]
	v_cvt_pk_bf16_f32 v106, v114, v115
	v_cvt_pk_bf16_f32 v107, v112, v113
	v_lshl_add_u64 v[110:111], v[110:111], 0, v[122:123]
	v_cvt_pk_bf16_f32 v108, v108, v109
	v_cvt_pk_bf16_f32 v109, v116, v117
	global_store_dwordx4 v[110:111], v[106:109], off nt
	v_pk_mul_f32 v[102:103], v[102:103], v[118:119] op_sel_hi:[1,0]
	v_pk_mul_f32 v[104:105], v[104:105], v[118:119] op_sel_hi:[1,0]
	v_pk_mul_f32 v[106:107], v[96:97], v[118:119] op_sel_hi:[1,0]
	v_pk_mul_f32 v[96:97], v[94:95], v[118:119] op_sel_hi:[1,0]
	v_cvt_pk_bf16_f32 v94, v102, v103
	v_cvt_pk_bf16_f32 v95, v104, v105
	s_nop 0
	v_cvt_pk_bf16_f32 v96, v96, v97
	v_cvt_pk_bf16_f32 v97, v106, v107
	ds_read_b32 v102, v161 offset:128
	global_store_dwordx4 v[110:111], v[94:97], off offset:256 nt
	s_waitcnt lgkmcnt(0)
	v_pk_mul_f32 v[98:99], v[98:99], v[102:103] op_sel_hi:[1,0]
	v_or_b32_e32 v94, 32, v163
	v_mad_i64_i32 v[94:95], s[26:27], v94, s31, v[142:143]
	v_pk_mul_f32 v[96:97], v[100:101], v[102:103] op_sel_hi:[1,0]
	v_pk_mul_f32 v[100:101], v[92:93], v[102:103] op_sel_hi:[1,0]
	v_pk_mul_f32 v[92:93], v[90:91], v[102:103] op_sel_hi:[1,0]
	v_cvt_pk_bf16_f32 v90, v98, v99
	v_cvt_pk_bf16_f32 v91, v96, v97
	v_lshl_add_u64 v[94:95], v[94:95], 0, v[122:123]
	v_cvt_pk_bf16_f32 v92, v92, v93
	v_cvt_pk_bf16_f32 v93, v100, v101
	global_store_dwordx4 v[94:95], v[90:93], off nt
	v_pk_mul_f32 v[86:87], v[86:87], v[102:103] op_sel_hi:[1,0]
	v_pk_mul_f32 v[88:89], v[88:89], v[102:103] op_sel_hi:[1,0]
	v_pk_mul_f32 v[90:91], v[80:81], v[102:103] op_sel_hi:[1,0]
	v_pk_mul_f32 v[80:81], v[78:79], v[102:103] op_sel_hi:[1,0]
	v_cvt_pk_bf16_f32 v78, v86, v87
	v_cvt_pk_bf16_f32 v79, v88, v89
	s_nop 0
	v_cvt_pk_bf16_f32 v80, v80, v81
	v_cvt_pk_bf16_f32 v81, v90, v91
	ds_read_b32 v86, v161 offset:192
	global_store_dwordx4 v[94:95], v[78:81], off offset:256 nt
	s_waitcnt lgkmcnt(0)
	v_pk_mul_f32 v[82:83], v[82:83], v[86:87] op_sel_hi:[1,0]
	v_or_b32_e32 v78, 48, v163
	v_mad_i64_i32 v[78:79], s[26:27], v78, s31, v[142:143]
	v_pk_mul_f32 v[80:81], v[84:85], v[86:87] op_sel_hi:[1,0]
	v_pk_mul_f32 v[84:85], v[76:77], v[86:87] op_sel_hi:[1,0]
	v_pk_mul_f32 v[76:77], v[74:75], v[86:87] op_sel_hi:[1,0]
	v_cvt_pk_bf16_f32 v74, v82, v83
	v_cvt_pk_bf16_f32 v75, v80, v81
	v_lshl_add_u64 v[78:79], v[78:79], 0, v[122:123]
	v_cvt_pk_bf16_f32 v76, v76, v77
	v_cvt_pk_bf16_f32 v77, v84, v85
	global_store_dwordx4 v[78:79], v[74:77], off nt
	v_pk_mul_f32 v[70:71], v[70:71], v[86:87] op_sel_hi:[1,0]
	v_pk_mul_f32 v[72:73], v[72:73], v[86:87] op_sel_hi:[1,0]
	v_pk_mul_f32 v[74:75], v[68:69], v[86:87] op_sel_hi:[1,0]
	v_pk_mul_f32 v[68:69], v[66:67], v[86:87] op_sel_hi:[1,0]
	v_cvt_pk_bf16_f32 v66, v70, v71
	v_cvt_pk_bf16_f32 v67, v72, v73
	s_nop 0
	v_cvt_pk_bf16_f32 v68, v68, v69
	v_cvt_pk_bf16_f32 v69, v74, v75
	ds_read_b32 v70, v161 offset:512
	global_store_dwordx4 v[78:79], v[66:69], off offset:256 nt
	s_waitcnt lgkmcnt(0)
; #define LAS __attribute__((address_space(3)))
; __device__ __forceinline__ unsigned cvt_pk_bf16(float lo, float hi) { unsigned r; asm volatile("v_cvt_pk_bf16_f32 %0, %1, %2" : "=v"(r) : "v"(lo), "v"(hi)); return r; }
; __device__ __forceinline__ float sigmoidf_(float v) { return __builtin_amdgcn_rcpf(1.f + __expf(-v)); }
; __device__ __forceinline__ float row_scale(const float* ssq, int row) {
;     const f32x4* p = (const f32x4*)(ssq + (size_t)row * 16); const f32x4 a = p[0], b = p[1], c = p[2], d = p[3];
;     const float s = ((a.x + a.y) + (a.z + a.w)) + ((b.x + b.y) + (b.z + b.w)) + ((c.x + c.y) + (c.z + c.w)) + ((d.x + d.y) + (d.z + d.w));
;     return rsqrtf(s * (1.f / DM) + EPS);
; }
;     __device__ __forceinline__ void operator()(const f32x4 (&acc)[2][2][4][2], const pg8::Unit& u, int wr, int wc, int fr, int fq, LAS unsigned char* sp) const {
;     ...
;         for (int ai = 0; ai < 2; ++ai)
; #pragma unroll
;             for (int m = 0; m < 4; ++m) {
;                 const int row = row0 + ai * 128 + m * 16; const float s = rsl[ai * 128 + m * 16];
; #pragma unroll
;                 for (int bj = 0; bj < 2; ++bj) {
;                     f32x4 v0 = acc[ai][bj][m][0] * s, v1 = acc[ai][bj][m][1] * s;
;                     const int col = colt + bj * 128 + cw0;
;                     if (act == 2) { const f32x4 b0 = *(const LAS f32x4*)(bsl + bj * 128 + cw0), b1 = *(const LAS f32x4*)(bsl + bj * 128 + cw0 + 4);
;                         v0 += b0; v1 += b1;
; #pragma unroll
;                         for (int j = 0; j < 4; ++j) { v0[j] = sigmoidf_(v0[j]); v1[j] = sigmoidf_(v1[j]); } }
;                     else if (act == 1) {
; #pragma unroll
;                         for (int j = 0; j < 4; ++j) { v0[j] = v0[j] * sigmoidf_(v0[j]); v1[j] = v1[j] * sigmoidf_(v1[j]); } }
;                     u32x4 w; w.x = cvt_pk_bf16(v0[0], v0[1]); w.y = cvt_pk_bf16(v0[2], v0[3]); w.z = cvt_pk_bf16(v1[0], v1[1]); w.w = cvt_pk_bf16(v1[2], v1[3]);
;                     *(u32x4*)(dst + (size_t)row * pitch + col) = w;
	v_pk_mul_f32 v[62:63], v[62:63], v[70:71] op_sel_hi:[1,0]
	v_add_u32_e32 v66, 0x80, v163
	v_mad_i64_i32 v[66:67], s[26:27], v66, s31, v[142:143]
	v_pk_mul_f32 v[64:65], v[64:65], v[70:71] op_sel_hi:[1,0]
	v_pk_mul_f32 v[68:69], v[60:61], v[70:71] op_sel_hi:[1,0]
	v_pk_mul_f32 v[60:61], v[58:59], v[70:71] op_sel_hi:[1,0]
	v_cvt_pk_bf16_f32 v58, v62, v63
	v_cvt_pk_bf16_f32 v59, v64, v65
	v_lshl_add_u64 v[62:63], v[66:67], 0, v[122:123]
	v_cvt_pk_bf16_f32 v60, v60, v61
	v_cvt_pk_bf16_f32 v61, v68, v69
	global_store_dwordx4 v[62:63], v[58:61], off nt
	v_pk_mul_f32 v[54:55], v[54:55], v[70:71] op_sel_hi:[1,0]
	v_pk_mul_f32 v[56:57], v[56:57], v[70:71] op_sel_hi:[1,0]
	v_pk_mul_f32 v[58:59], v[48:49], v[70:71] op_sel_hi:[1,0]
	v_pk_mul_f32 v[48:49], v[46:47], v[70:71] op_sel_hi:[1,0]
	v_cvt_pk_bf16_f32 v46, v54, v55
	v_cvt_pk_bf16_f32 v47, v56, v57
	s_nop 0
	v_cvt_pk_bf16_f32 v48, v48, v49
	v_cvt_pk_bf16_f32 v49, v58, v59
	ds_read_b32 v54, v161 offset:576
	global_store_dwordx4 v[62:63], v[46:49], off offset:256 nt
	s_waitcnt lgkmcnt(0)
	v_pk_mul_f32 v[50:51], v[50:51], v[54:55] op_sel_hi:[1,0]
	v_add_u32_e32 v46, 0x90, v163
	v_mad_i64_i32 v[46:47], s[26:27], v46, s31, v[142:143]
	v_pk_mul_f32 v[48:49], v[52:53], v[54:55] op_sel_hi:[1,0]
	v_pk_mul_f32 v[52:53], v[44:45], v[54:55] op_sel_hi:[1,0]
	v_pk_mul_f32 v[44:45], v[42:43], v[54:55] op_sel_hi:[1,0]
	v_cvt_pk_bf16_f32 v42, v50, v51
	v_cvt_pk_bf16_f32 v43, v48, v49
	v_lshl_add_u64 v[46:47], v[46:47], 0, v[122:123]
	v_cvt_pk_bf16_f32 v44, v44, v45
	v_cvt_pk_bf16_f32 v45, v52, v53
	global_store_dwordx4 v[46:47], v[42:45], off nt
	v_pk_mul_f32 v[38:39], v[38:39], v[54:55] op_sel_hi:[1,0]
	v_pk_mul_f32 v[40:41], v[40:41], v[54:55] op_sel_hi:[1,0]
	v_pk_mul_f32 v[42:43], v[32:33], v[54:55] op_sel_hi:[1,0]
	v_pk_mul_f32 v[32:33], v[30:31], v[54:55] op_sel_hi:[1,0]
	v_cvt_pk_bf16_f32 v30, v38, v39
	v_cvt_pk_bf16_f32 v31, v40, v41
	s_nop 0
	v_cvt_pk_bf16_f32 v32, v32, v33
	v_cvt_pk_bf16_f32 v33, v42, v43
	ds_read_b32 v38, v161 offset:640
	global_store_dwordx4 v[46:47], v[30:33], off offset:256 nt
	s_waitcnt lgkmcnt(0)
	v_pk_mul_f32 v[34:35], v[34:35], v[38:39] op_sel_hi:[1,0]
	v_add_u32_e32 v30, 0xa0, v163
	v_mad_i64_i32 v[30:31], s[26:27], v30, s31, v[142:143]
	v_pk_mul_f32 v[32:33], v[36:37], v[38:39] op_sel_hi:[1,0]
	v_pk_mul_f32 v[36:37], v[28:29], v[38:39] op_sel_hi:[1,0]
	v_pk_mul_f32 v[28:29], v[26:27], v[38:39] op_sel_hi:[1,0]
	v_cvt_pk_bf16_f32 v26, v34, v35
	v_cvt_pk_bf16_f32 v27, v32, v33
	v_lshl_add_u64 v[30:31], v[30:31], 0, v[122:123]
	v_cvt_pk_bf16_f32 v28, v28, v29
	v_cvt_pk_bf16_f32 v29, v36, v37
	global_store_dwordx4 v[30:31], v[26:29], off nt
	v_pk_mul_f32 v[22:23], v[22:23], v[38:39] op_sel_hi:[1,0]
	v_pk_mul_f32 v[24:25], v[24:25], v[38:39] op_sel_hi:[1,0]
	v_pk_mul_f32 v[26:27], v[16:17], v[38:39] op_sel_hi:[1,0]
	v_pk_mul_f32 v[16:17], v[14:15], v[38:39] op_sel_hi:[1,0]
	v_cvt_pk_bf16_f32 v14, v22, v23
	v_cvt_pk_bf16_f32 v15, v24, v25
	s_nop 0
	v_cvt_pk_bf16_f32 v16, v16, v17
	v_cvt_pk_bf16_f32 v17, v26, v27
	ds_read_b32 v22, v161 offset:704
	global_store_dwordx4 v[30:31], v[14:17], off offset:256 nt
	s_waitcnt lgkmcnt(0)
	v_pk_mul_f32 v[18:19], v[18:19], v[22:23] op_sel_hi:[1,0]
	v_add_u32_e32 v14, 0xb0, v163
	v_mad_i64_i32 v[14:15], s[26:27], v14, s31, v[142:143]
	v_pk_mul_f32 v[16:17], v[20:21], v[22:23] op_sel_hi:[1,0]
	v_pk_mul_f32 v[20:21], v[12:13], v[22:23] op_sel_hi:[1,0]
	v_pk_mul_f32 v[12:13], v[10:11], v[22:23] op_sel_hi:[1,0]
	v_cvt_pk_bf16_f32 v10, v18, v19
	v_cvt_pk_bf16_f32 v11, v16, v17
	v_lshl_add_u64 v[14:15], v[14:15], 0, v[122:123]
	v_cvt_pk_bf16_f32 v12, v12, v13
	v_cvt_pk_bf16_f32 v13, v20, v21
	global_store_dwordx4 v[14:15], v[10:13], off nt
	v_pk_mul_f32 v[8:9], v[8:9], v[22:23] op_sel_hi:[1,0]
	v_pk_mul_f32 v[6:7], v[6:7], v[22:23] op_sel_hi:[1,0]
	v_pk_mul_f32 v[10:11], v[4:5], v[22:23] op_sel_hi:[1,0]
	v_pk_mul_f32 v[4:5], v[2:3], v[22:23] op_sel_hi:[1,0]
	v_cvt_pk_bf16_f32 v2, v6, v7
	v_cvt_pk_bf16_f32 v3, v8, v9
	s_nop 0
	v_cvt_pk_bf16_f32 v4, v4, v5
	v_cvt_pk_bf16_f32 v5, v10, v11
	global_store_dwordx4 v[14:15], v[2:5], off offset:256 nt
	s_cbranch_vccnz .LBB0_26
	s_and_saveexec_b64 s[6:7], s[4:5]
	s_cbranch_execz .LBB0_36
	s_lshl_b32 s19, s67, 11
	s_and_b32 s19, s19, 0x800
	s_waitcnt vmcnt(16)
	v_mov_b32_e32 v2, v198
	v_mov_b32_e32 v3, v199
	v_mov_b32_e32 v4, v200
	v_mov_b32_e32 v5, v201
	v_mov_b32_e32 v6, v202
	v_mov_b32_e32 v7, v203
	v_mov_b32_e32 v8, v204
	v_mov_b32_e32 v9, v205
	v_mov_b32_e32 v10, v206
	v_mov_b32_e32 v11, v207
	v_mov_b32_e32 v12, v208
	v_mov_b32_e32 v13, v209
	v_mov_b32_e32 v14, v210
	v_mov_b32_e32 v15, v211
	v_mov_b32_e32 v16, v212
	v_mov_b32_e32 v17, v213
	v_add_f32_e32 v6, v6, v7
	v_add_f32_e32 v8, v8, v9
	v_mov_b32_e32 v18, v15
	v_mov_b32_e32 v19, v16
	v_mov_b32_e32 v15, v17
	v_mov_b32_e32 v16, v11
	v_mov_b32_e32 v17, v12
	v_mov_b32_e32 v11, v13
	v_pk_add_f32 v[14:15], v[18:19], v[14:15]
	v_pk_add_f32 v[10:11], v[16:17], v[10:11]
	v_pk_add_f32 v[14:15], v[14:15], v[14:15] op_sel:[0,1] op_sel_hi:[1,0]
	v_pk_add_f32 v[10:11], v[10:11], v[10:11] op_sel:[0,1] op_sel_hi:[1,0]
	v_mov_b32_e32 v15, v2
	v_mov_b32_e32 v11, v3
	v_mov_b32_e32 v7, v4
	v_mov_b32_e32 v9, v5
	v_pk_add_f32 v[2:3], v[14:15], v[10:11]
	v_pk_add_f32 v[4:5], v[6:7], v[8:9]
	s_nop 0
	v_pk_add_f32 v[2:3], v[2:3], v[4:5]
	s_nop 0
	v_add_f32_e32 v2, v2, v3
	v_fmamk_f32 v2, v2, 0x3a800000, v184
	v_cmp_gt_f32_e32 vcc, s74, v2
	v_mul_f32_e32 v3, 0x4b800000, v2
	s_nop 0
	v_cndmask_b32_e32 v2, v2, v3, vcc
	v_rsq_f32_e32 v2, v2
	s_nop 0
	v_mul_f32_e32 v3, 0x45800000, v2
	v_cndmask_b32_e32 v2, v2, v3, vcc
	v_add_u32_e32 v3, s19, v158
	ds_write_b32 v3, v2
